# micro-trims: attention loop-head m0 save/restore and dead branch removed; redundant lgkmcnt(0) after the GEMM pre-MFMA barriers removed
# speedup vs baseline: 1.0108x; 1.0108x over previous
; #define PG8_STAGE(bufoff, gbase, voff) do { _Pragma("unroll") for (int _i = 0; _i < 2; ++_i) \
;         __builtin_amdgcn_global_load_lds((const unsigned*)((const char*)(gbase) + (voff)[_i]), (PG8_LAS unsigned*)(lds + (bufoff) + ldsw + _i * 8192), 16, 0, 0); } while (0)
; #define PG8_LDA(dst, b, h) do { _Pragma("unroll") for (int m = 0; m < 4; ++m) _Pragma("unroll") for (int k = 0; k < 2; ++k) dst[m][k] = *(const PG8_LAS bf16x8*)(lds + PG8_SA(b, h) + aoff + m * 2048 + k * 1024); } while (0)
; #define PG8_MMA(ai, bj, At, Bt) do { __builtin_amdgcn_s_setprio(1); _Pragma("unroll") for (int m = 0; m < 4; ++m) _Pragma("unroll") for (int n = 0; n < 2; ++n) _Pragma("unroll") for (int k = 0; k < 2; ++k) \
;         acc[ai][bj][m][n] = __builtin_amdgcn_mfma_f32_16x16x32_bf16(Bt[n][k], At[m][k], acc[ai][bj][m][n], 0, 0, 0); __builtin_amdgcn_s_setprio(0); } while (0)
; #define PG8_WAIT_V(n) asm volatile("s_waitcnt vmcnt(" #n ")" ::: "memory")
; #define PG8_WAIT_L(n) asm volatile("s_waitcnt lgkmcnt(" #n ")" ::: "memory")
; #define PG8_BAR __builtin_amdgcn_s_barrier()
; #define PG8_SCHED __builtin_amdgcn_sched_barrier(0)
; template <class Epi, class Sched, bool ALIGN_EPI = false, bool SP2 = false>
; __device__ __forceinline__ void gemm_phase(PG8_LAS unsigned char* lds, const Gemm g, const Sched& S, const Epi& E, const int tid) {
;     ...
;             PG8_WAIT_V(8); PG8_WAIT_L(0); PG8_BAR; PG8_MMA(0, 0, At, B0); PG8_MMA(0, 1, At, B1); PG8_BAR; PG8_SCHED;
;             PG8_LDA(At, 0, 1); PG8_STAGE(PG8_SB(0, 0), b2, voffB); PG8_STAGE(PG8_SB(0, 1), b2 + hstepB, voffB); PG8_STAGE(PG8_SA(0, 0), a2, voffA);
.Lg_done1:
	s_waitcnt lgkmcnt(0)
	s_barrier
	s_setprio 1
	v_mfma_f32_16x16x32_bf16 v[126:129], v[150:153], v[212:215], v[126:129]
	v_mfma_f32_16x16x32_bf16 v[122:125], v[164:167], v[212:215], v[122:125]
	v_mfma_f32_16x16x32_bf16 v[118:121], v[150:153], v[220:223], v[118:121]
	v_mfma_f32_16x16x32_bf16 v[114:117], v[164:167], v[220:223], v[114:117]
	v_mfma_f32_16x16x32_bf16 v[106:109], v[150:153], v[228:231], v[106:109]
	v_mfma_f32_16x16x32_bf16 v[98:101], v[164:167], v[228:231], v[98:101]
	v_mfma_f32_16x16x32_bf16 v[90:93], v[150:153], v[236:239], v[90:93]
	v_mfma_f32_16x16x32_bf16 v[82:85], v[164:167], v[236:239], v[82:85]
	v_mfma_f32_16x16x32_bf16 v[126:129], v[160:163], v[216:219], v[126:129]
	v_mfma_f32_16x16x32_bf16 v[122:125], v[168:171], v[216:219], v[122:125]
	v_mfma_f32_16x16x32_bf16 v[118:121], v[160:163], v[224:227], v[118:121]
	v_mfma_f32_16x16x32_bf16 v[114:117], v[168:171], v[224:227], v[114:117]
	v_mfma_f32_16x16x32_bf16 v[106:109], v[160:163], v[232:235], v[106:109]
	v_mfma_f32_16x16x32_bf16 v[98:101], v[168:171], v[232:235], v[98:101]
	v_mfma_f32_16x16x32_bf16 v[90:93], v[160:163], v[240:243], v[90:93]
	v_mfma_f32_16x16x32_bf16 v[82:85], v[168:171], v[240:243], v[82:85]
	s_setprio 0
	s_setprio 1
	v_mfma_f32_16x16x32_bf16 v[110:113], v[172:175], v[212:215], v[110:113]
	v_mfma_f32_16x16x32_bf16 v[102:105], v[180:183], v[212:215], v[102:105]
	v_mfma_f32_16x16x32_bf16 v[94:97], v[172:175], v[220:223], v[94:97]
	v_mfma_f32_16x16x32_bf16 v[86:89], v[180:183], v[220:223], v[86:89]
	v_mfma_f32_16x16x32_bf16 v[78:81], v[172:175], v[228:231], v[78:81]
	v_mfma_f32_16x16x32_bf16 v[74:77], v[180:183], v[228:231], v[74:77]
	v_mfma_f32_16x16x32_bf16 v[70:73], v[172:175], v[236:239], v[70:73]
	v_mfma_f32_16x16x32_bf16 v[66:69], v[180:183], v[236:239], v[66:69]
	v_mfma_f32_16x16x32_bf16 v[110:113], v[176:179], v[216:219], v[110:113]
	v_mfma_f32_16x16x32_bf16 v[102:105], v[208:211], v[216:219], v[102:105]
	v_mfma_f32_16x16x32_bf16 v[94:97], v[176:179], v[224:227], v[94:97]
	v_mfma_f32_16x16x32_bf16 v[86:89], v[208:211], v[224:227], v[86:89]
	v_mfma_f32_16x16x32_bf16 v[78:81], v[176:179], v[232:235], v[78:81]
	v_mfma_f32_16x16x32_bf16 v[74:77], v[208:211], v[232:235], v[74:77]
	v_mfma_f32_16x16x32_bf16 v[70:73], v[176:179], v[240:243], v[70:73]
	v_mfma_f32_16x16x32_bf16 v[66:69], v[208:211], v[240:243], v[66:69]
	s_setprio 0
	s_barrier
	s_add_i32 s22, s22, s43
	v_lshl_add_u64 v[144:145], vcc, 0, v[134:135]
	s_mov_b32 m0, s22
	ds_read_b128 v[212:215], v158 offset:16384
	ds_read_b128 v[216:219], v158 offset:17408
	ds_read_b128 v[220:223], v158 offset:18432
	ds_read_b128 v[224:227], v158 offset:19456
	ds_read_b128 v[228:231], v158 offset:20480
	ds_read_b128 v[232:235], v158 offset:21504
	ds_read_b128 v[236:239], v158 offset:22528
	ds_read_b128 v[240:243], v158 offset:23552
	global_load_lds_dwordx4 v[144:145], off
	s_add_i32 m0, s22, 0x2000
	v_lshl_add_u64 v[154:155], vcc, 0, v[130:131]
	s_add_u32 vcc_lo, vcc_lo, s41
	s_addc_u32 vcc_hi, vcc_hi, 0
	s_add_i32 s22, s23, s43
	global_load_lds_dwordx4 v[154:155], off
	v_lshl_add_u64 v[184:185], vcc, 0, v[134:135]
	s_mov_b32 m0, s22
	v_lshl_add_u64 v[244:245], vcc, 0, v[130:131]
	global_load_lds_dwordx4 v[184:185], off
	s_add_i32 m0, s22, 0x2000
	v_lshl_add_u64 v[246:247], s[56:57], 0, v[136:137]
	global_load_lds_dwordx4 v[244:245], off
	s_mov_b32 m0, s96
	v_lshl_add_u64 v[248:249], s[56:57], 0, v[132:133]
	global_load_lds_dwordx4 v[246:247], off
	s_mov_b32 m0, s97
	s_nop 0
	global_load_lds_dwordx4 v[248:249], off
	s_cmp_eq_u32 s100, 0
	s_cbranch_scc1 .Lg_norm2
	s_sub_u32 s100, s100, 1
	s_waitcnt vmcnt(24)
	s_branch .Lg_done2

; #define PG8_STAGE(bufoff, gbase, voff) do { _Pragma("unroll") for (int _i = 0; _i < 2; ++_i) \
;         __builtin_amdgcn_global_load_lds((const unsigned*)((const char*)(gbase) + (voff)[_i]), (PG8_LAS unsigned*)(lds + (bufoff) + ldsw + _i * 8192), 16, 0, 0); } while (0)
; #define PG8_LDA(dst, b, h) do { _Pragma("unroll") for (int m = 0; m < 4; ++m) _Pragma("unroll") for (int k = 0; k < 2; ++k) dst[m][k] = *(const PG8_LAS bf16x8*)(lds + PG8_SA(b, h) + aoff + m * 2048 + k * 1024); } while (0)
; #define PG8_LDB(dst, b, h) do { _Pragma("unroll") for (int n = 0; n < 2; ++n) _Pragma("unroll") for (int k = 0; k < 2; ++k) dst[n][k] = *(const PG8_LAS bf16x8*)(lds + PG8_SB(b, h) + boff + n * 2048 + k * 1024); } while (0)
; #define PG8_MMA(ai, bj, At, Bt) do { __builtin_amdgcn_s_setprio(1); _Pragma("unroll") for (int m = 0; m < 4; ++m) _Pragma("unroll") for (int n = 0; n < 2; ++n) _Pragma("unroll") for (int k = 0; k < 2; ++k) \
;         acc[ai][bj][m][n] = __builtin_amdgcn_mfma_f32_16x16x32_bf16(Bt[n][k], At[m][k], acc[ai][bj][m][n], 0, 0, 0); __builtin_amdgcn_s_setprio(0); } while (0)
; #define PG8_WAIT_V(n) asm volatile("s_waitcnt vmcnt(" #n ")" ::: "memory")
; #define PG8_WAIT_L(n) asm volatile("s_waitcnt lgkmcnt(" #n ")" ::: "memory")
; #define PG8_BAR __builtin_amdgcn_s_barrier()
; #define PG8_SCHED __builtin_amdgcn_sched_barrier(0)
; template <class Epi, class Sched, bool ALIGN_EPI = false, bool SP2 = false>
; __device__ __forceinline__ void gemm_phase(PG8_LAS unsigned char* lds, const Gemm g, const Sched& S, const Epi& E, const int tid) {
;     ...
;             PG8_WAIT_V(8); PG8_WAIT_L(0); PG8_BAR; PG8_MMA(1, 0, At, B0); PG8_MMA(1, 1, At, B1); PG8_BAR; PG8_SCHED;
;             PG8_LDB(B0, 1, 0); PG8_LDB(B1, 1, 1); PG8_SCHED; PG8_LDA(At, 1, 0); PG8_STAGE(PG8_SA(0, 1), a2 + hstepA, voffA);
;             PG8_WAIT_V(8); PG8_WAIT_L(0); PG8_BAR; PG8_MMA(0, 0, At, B0); PG8_MMA(0, 1, At, B1); PG8_BAR; PG8_SCHED;
.Lg_done2:
	s_waitcnt lgkmcnt(0)
	s_barrier
	s_setprio 1
	v_mfma_f32_16x16x32_bf16 v[62:65], v[150:153], v[212:215], v[62:65]
	v_mfma_f32_16x16x32_bf16 v[58:61], v[164:167], v[212:215], v[58:61]
	v_mfma_f32_16x16x32_bf16 v[54:57], v[150:153], v[220:223], v[54:57]
	v_mfma_f32_16x16x32_bf16 v[50:53], v[164:167], v[220:223], v[50:53]
	v_mfma_f32_16x16x32_bf16 v[42:45], v[150:153], v[228:231], v[42:45]
	v_mfma_f32_16x16x32_bf16 v[34:37], v[164:167], v[228:231], v[34:37]
	v_mfma_f32_16x16x32_bf16 v[26:29], v[150:153], v[236:239], v[26:29]
	v_mfma_f32_16x16x32_bf16 v[18:21], v[164:167], v[236:239], v[18:21]
	v_mfma_f32_16x16x32_bf16 v[62:65], v[160:163], v[216:219], v[62:65]
	v_mfma_f32_16x16x32_bf16 v[58:61], v[168:171], v[216:219], v[58:61]
	v_mfma_f32_16x16x32_bf16 v[54:57], v[160:163], v[224:227], v[54:57]
	v_mfma_f32_16x16x32_bf16 v[50:53], v[168:171], v[224:227], v[50:53]
	v_mfma_f32_16x16x32_bf16 v[42:45], v[160:163], v[232:235], v[42:45]
	v_mfma_f32_16x16x32_bf16 v[34:37], v[168:171], v[232:235], v[34:37]
	v_mfma_f32_16x16x32_bf16 v[26:29], v[160:163], v[240:243], v[26:29]
	v_mfma_f32_16x16x32_bf16 v[18:21], v[168:171], v[240:243], v[18:21]
	s_setprio 0
	s_setprio 1
	v_mfma_f32_16x16x32_bf16 v[46:49], v[172:175], v[212:215], v[46:49]
	v_mfma_f32_16x16x32_bf16 v[38:41], v[180:183], v[212:215], v[38:41]
	v_mfma_f32_16x16x32_bf16 v[30:33], v[172:175], v[220:223], v[30:33]
	v_mfma_f32_16x16x32_bf16 v[22:25], v[180:183], v[220:223], v[22:25]
	v_mfma_f32_16x16x32_bf16 v[14:17], v[172:175], v[228:231], v[14:17]
	v_mfma_f32_16x16x32_bf16 v[10:13], v[180:183], v[228:231], v[10:13]
	v_mfma_f32_16x16x32_bf16 v[6:9], v[172:175], v[236:239], v[6:9]
	v_mfma_f32_16x16x32_bf16 v[2:5], v[180:183], v[236:239], v[2:5]
	v_mfma_f32_16x16x32_bf16 v[46:49], v[176:179], v[216:219], v[46:49]
	v_mfma_f32_16x16x32_bf16 v[38:41], v[208:211], v[216:219], v[38:41]
	v_mfma_f32_16x16x32_bf16 v[30:33], v[176:179], v[224:227], v[30:33]
	v_mfma_f32_16x16x32_bf16 v[22:25], v[208:211], v[224:227], v[22:25]
	v_mfma_f32_16x16x32_bf16 v[14:17], v[176:179], v[232:235], v[14:17]
	v_mfma_f32_16x16x32_bf16 v[10:13], v[208:211], v[232:235], v[10:13]
	v_mfma_f32_16x16x32_bf16 v[6:9], v[176:179], v[240:243], v[6:9]
	v_mfma_f32_16x16x32_bf16 v[2:5], v[208:211], v[240:243], v[2:5]
	s_setprio 0
	s_barrier
	s_add_i32 s22, 0, 0x18000
	v_add_u32_e32 v159, s22, v156
	s_add_i32 s23, 0, 0x1c000
	ds_read_b128 v[150:153], v159
	ds_read_b128 v[160:163], v159 offset:1024
	ds_read_b128 v[164:167], v159 offset:2048
	ds_read_b128 v[168:171], v159 offset:3072
	v_add_u32_e32 v159, s23, v156
	ds_read_b128 v[172:175], v159
	ds_read_b128 v[176:179], v159 offset:1024
	ds_read_b128 v[180:183], v159 offset:2048
	ds_read_b128 v[208:211], v159 offset:3072
	s_add_u32 s56, s56, s50
	s_addc_u32 s57, s57, 0
	s_mov_b32 m0, s0
	v_lshl_add_u64 v[250:251], s[56:57], 0, v[136:137]
	ds_read_b128 v[212:215], v158 offset:32768
	ds_read_b128 v[216:219], v158 offset:33792
	ds_read_b128 v[220:223], v158 offset:34816
	ds_read_b128 v[224:227], v158 offset:35840
	ds_read_b128 v[228:231], v158 offset:36864
	ds_read_b128 v[232:235], v158 offset:37888
	ds_read_b128 v[236:239], v158 offset:38912
	ds_read_b128 v[240:243], v158 offset:39936
	global_load_lds_dwordx4 v[250:251], off
	v_lshl_add_u64 v[250:251], s[56:57], 0, v[132:133]
	s_mov_b32 m0, s1
	s_nop 0
	global_load_lds_dwordx4 v[250:251], off
	s_waitcnt vmcnt(8)
	s_waitcnt lgkmcnt(0)
	s_barrier
	s_setprio 1
	v_mfma_f32_16x16x32_bf16 v[126:129], v[150:153], v[212:215], v[126:129]
	v_mfma_f32_16x16x32_bf16 v[122:125], v[164:167], v[212:215], v[122:125]
	v_mfma_f32_16x16x32_bf16 v[118:121], v[150:153], v[220:223], v[118:121]
	v_mfma_f32_16x16x32_bf16 v[114:117], v[164:167], v[220:223], v[114:117]
	v_mfma_f32_16x16x32_bf16 v[106:109], v[150:153], v[228:231], v[106:109]
	v_mfma_f32_16x16x32_bf16 v[98:101], v[164:167], v[228:231], v[98:101]
	v_mfma_f32_16x16x32_bf16 v[90:93], v[150:153], v[236:239], v[90:93]
	v_mfma_f32_16x16x32_bf16 v[82:85], v[164:167], v[236:239], v[82:85]
	v_mfma_f32_16x16x32_bf16 v[126:129], v[160:163], v[216:219], v[126:129]
	v_mfma_f32_16x16x32_bf16 v[122:125], v[168:171], v[216:219], v[122:125]
	v_mfma_f32_16x16x32_bf16 v[118:121], v[160:163], v[224:227], v[118:121]
	v_mfma_f32_16x16x32_bf16 v[114:117], v[168:171], v[224:227], v[114:117]
	v_mfma_f32_16x16x32_bf16 v[106:109], v[160:163], v[232:235], v[106:109]
	v_mfma_f32_16x16x32_bf16 v[98:101], v[168:171], v[232:235], v[98:101]
	v_mfma_f32_16x16x32_bf16 v[90:93], v[160:163], v[240:243], v[90:93]
	v_mfma_f32_16x16x32_bf16 v[82:85], v[168:171], v[240:243], v[82:85]
	s_setprio 0
	s_setprio 1
	v_mfma_f32_16x16x32_bf16 v[110:113], v[172:175], v[212:215], v[110:113]
	v_mfma_f32_16x16x32_bf16 v[102:105], v[180:183], v[212:215], v[102:105]
	v_mfma_f32_16x16x32_bf16 v[94:97], v[172:175], v[220:223], v[94:97]
	v_mfma_f32_16x16x32_bf16 v[86:89], v[180:183], v[220:223], v[86:89]
	v_mfma_f32_16x16x32_bf16 v[78:81], v[172:175], v[228:231], v[78:81]
	v_mfma_f32_16x16x32_bf16 v[74:77], v[180:183], v[228:231], v[74:77]
	v_mfma_f32_16x16x32_bf16 v[70:73], v[172:175], v[236:239], v[70:73]
	v_mfma_f32_16x16x32_bf16 v[66:69], v[180:183], v[236:239], v[66:69]
	v_mfma_f32_16x16x32_bf16 v[110:113], v[176:179], v[216:219], v[110:113]
	v_mfma_f32_16x16x32_bf16 v[102:105], v[208:211], v[216:219], v[102:105]
	v_mfma_f32_16x16x32_bf16 v[94:97], v[176:179], v[224:227], v[94:97]
	v_mfma_f32_16x16x32_bf16 v[86:89], v[208:211], v[224:227], v[86:89]
	v_mfma_f32_16x16x32_bf16 v[78:81], v[176:179], v[232:235], v[78:81]
	v_mfma_f32_16x16x32_bf16 v[74:77], v[208:211], v[232:235], v[74:77]
	v_mfma_f32_16x16x32_bf16 v[70:73], v[176:179], v[240:243], v[70:73]
	v_mfma_f32_16x16x32_bf16 v[66:69], v[208:211], v[240:243], v[66:69]
	s_setprio 0
	s_barrier
; #define PG8_STAGE(bufoff, gbase, voff) do { _Pragma("unroll") for (int _i = 0; _i < 2; ++_i) \
;         __builtin_amdgcn_global_load_lds((const unsigned*)((const char*)(gbase) + (voff)[_i]), (PG8_LAS unsigned*)(lds + (bufoff) + ldsw + _i * 8192), 16, 0, 0); } while (0)
; #define PG8_LDA(dst, b, h) do { _Pragma("unroll") for (int m = 0; m < 4; ++m) _Pragma("unroll") for (int k = 0; k < 2; ++k) dst[m][k] = *(const PG8_LAS bf16x8*)(lds + PG8_SA(b, h) + aoff + m * 2048 + k * 1024); } while (0)
; #define PG8_MMA(ai, bj, At, Bt) do { __builtin_amdgcn_s_setprio(1); _Pragma("unroll") for (int m = 0; m < 4; ++m) _Pragma("unroll") for (int n = 0; n < 2; ++n) _Pragma("unroll") for (int k = 0; k < 2; ++k) \
;         acc[ai][bj][m][n] = __builtin_amdgcn_mfma_f32_16x16x32_bf16(Bt[n][k], At[m][k], acc[ai][bj][m][n], 0, 0, 0); __builtin_amdgcn_s_setprio(0); } while (0)
; #define PG8_WAIT_V(n) asm volatile("s_waitcnt vmcnt(" #n ")" ::: "memory")
; #define PG8_WAIT_L(n) asm volatile("s_waitcnt lgkmcnt(" #n ")" ::: "memory")
; #define PG8_BAR __builtin_amdgcn_s_barrier()
; #define PG8_SCHED __builtin_amdgcn_sched_barrier(0)
;     __device__ __forceinline__ void operator()(const f32x4 (&acc)[2][2][4][2], const Unit& u, int wr, int wc, int fr, int fq) const {
;     ...
;                 for (int bj = 0; bj < 2; ++bj) { f32x4 v0 = acc[ai][bj][m][0] + bv[bj][0], v1 = acc[ai][bj][m][1] + bv[bj][1];
; template <class Epi, class Sched, bool ALIGN_EPI = false, bool SP2 = false>
; __device__ __forceinline__ void gemm_phase(PG8_LAS unsigned char* lds, const Gemm g, const Sched& S, const Epi& E, const int tid) {
;     ...
;             PG8_LDA(At, 1, 1); PG8_STAGE(PG8_SB(1, 0), b3, voffB); PG8_STAGE(PG8_SB(1, 1), b3 + hstepB, voffB); PG8_STAGE(PG8_SA(1, 0), a3, voffA);
;             PG8_WAIT_V(8); PG8_WAIT_L(0); PG8_BAR; PG8_MMA(1, 0, At, B0); PG8_MMA(1, 1, At, B1); PG8_BAR; PG8_SCHED;
	s_add_i32 s22, s22, s43
	v_lshl_add_u64 v[144:145], v[144:145], 0, s[52:53]
	s_mov_b32 m0, s22
	ds_read_b128 v[212:215], v158 offset:49152
	ds_read_b128 v[216:219], v158 offset:50176
	ds_read_b128 v[220:223], v158 offset:51200
	ds_read_b128 v[224:227], v158 offset:52224
	ds_read_b128 v[228:231], v158 offset:53248
	ds_read_b128 v[232:235], v158 offset:54272
	ds_read_b128 v[236:239], v158 offset:55296
	ds_read_b128 v[240:243], v158 offset:56320
	global_load_lds_dwordx4 v[144:145], off
	v_lshl_add_u64 v[144:145], v[154:155], 0, s[52:53]
	s_add_i32 m0, s22, 0x2000
	s_add_i32 s22, s23, s43
	global_load_lds_dwordx4 v[144:145], off
	v_lshl_add_u64 v[144:145], v[184:185], 0, s[52:53]
	s_mov_b32 m0, s22
	s_nop 0
	global_load_lds_dwordx4 v[144:145], off
	v_lshl_add_u64 v[144:145], v[244:245], 0, s[52:53]
	s_add_i32 m0, s22, 0x2000
	s_nop 0
	global_load_lds_dwordx4 v[144:145], off
	v_lshl_add_u64 v[144:145], v[246:247], 0, s[52:53]
	s_mov_b32 m0, s98
	s_nop 0
	global_load_lds_dwordx4 v[144:145], off
	v_lshl_add_u64 v[144:145], v[248:249], 0, s[52:53]
	s_mov_b32 m0, s99
	s_nop 0
	global_load_lds_dwordx4 v[144:145], off
	s_waitcnt vmcnt(8)
	s_waitcnt lgkmcnt(0)
	s_barrier
	s_setprio 1
	v_mfma_f32_16x16x32_bf16 v[62:65], v[150:153], v[212:215], v[62:65]
	v_mfma_f32_16x16x32_bf16 v[58:61], v[164:167], v[212:215], v[58:61]
	v_mfma_f32_16x16x32_bf16 v[54:57], v[150:153], v[220:223], v[54:57]
	v_mfma_f32_16x16x32_bf16 v[50:53], v[164:167], v[220:223], v[50:53]
	v_mfma_f32_16x16x32_bf16 v[42:45], v[150:153], v[228:231], v[42:45]
	v_mfma_f32_16x16x32_bf16 v[34:37], v[164:167], v[228:231], v[34:37]
	v_mfma_f32_16x16x32_bf16 v[26:29], v[150:153], v[236:239], v[26:29]
	v_mfma_f32_16x16x32_bf16 v[18:21], v[164:167], v[236:239], v[18:21]
	v_mfma_f32_16x16x32_bf16 v[62:65], v[160:163], v[216:219], v[62:65]
	v_mfma_f32_16x16x32_bf16 v[58:61], v[168:171], v[216:219], v[58:61]
	v_mfma_f32_16x16x32_bf16 v[54:57], v[160:163], v[224:227], v[54:57]
	v_mfma_f32_16x16x32_bf16 v[50:53], v[168:171], v[224:227], v[50:53]
	v_mfma_f32_16x16x32_bf16 v[42:45], v[160:163], v[232:235], v[42:45]
	v_mfma_f32_16x16x32_bf16 v[34:37], v[168:171], v[232:235], v[34:37]
	v_mfma_f32_16x16x32_bf16 v[26:29], v[160:163], v[240:243], v[26:29]
	v_mfma_f32_16x16x32_bf16 v[18:21], v[168:171], v[240:243], v[18:21]
	s_setprio 0
	s_setprio 1
	v_mfma_f32_16x16x32_bf16 v[46:49], v[172:175], v[212:215], v[46:49]
	v_mfma_f32_16x16x32_bf16 v[38:41], v[180:183], v[212:215], v[38:41]
	v_mfma_f32_16x16x32_bf16 v[30:33], v[172:175], v[220:223], v[30:33]
	v_mfma_f32_16x16x32_bf16 v[22:25], v[180:183], v[220:223], v[22:25]
	v_mfma_f32_16x16x32_bf16 v[14:17], v[172:175], v[228:231], v[14:17]
	v_mfma_f32_16x16x32_bf16 v[10:13], v[180:183], v[228:231], v[10:13]
	v_mfma_f32_16x16x32_bf16 v[6:9], v[172:175], v[236:239], v[6:9]
	v_mfma_f32_16x16x32_bf16 v[2:5], v[180:183], v[236:239], v[2:5]
	v_mfma_f32_16x16x32_bf16 v[46:49], v[176:179], v[216:219], v[46:49]
	v_mfma_f32_16x16x32_bf16 v[38:41], v[208:211], v[216:219], v[38:41]
	v_mfma_f32_16x16x32_bf16 v[30:33], v[176:179], v[224:227], v[30:33]
	v_mfma_f32_16x16x32_bf16 v[22:25], v[208:211], v[224:227], v[22:25]
	v_mfma_f32_16x16x32_bf16 v[14:17], v[176:179], v[232:235], v[14:17]
	v_mfma_f32_16x16x32_bf16 v[10:13], v[208:211], v[232:235], v[10:13]
	v_mfma_f32_16x16x32_bf16 v[6:9], v[176:179], v[240:243], v[6:9]
	v_mfma_f32_16x16x32_bf16 v[2:5], v[208:211], v[240:243], v[2:5]
	s_setprio 0
	s_barrier
	s_add_u32 s90, s90, 0x100
	s_addc_u32 s91, s91, 0
	s_add_u32 s25, s25, 0x100
	s_addc_u32 s92, s92, 0
	s_cmp_ge_u32 s93, s33
	s_mov_b32 s56, s93
	s_cbranch_scc0 .LBB0_67
	v_pk_add_f32 v[128:129], v[128:129], 0 op_sel_hi:[1,0]
	v_pk_add_f32 v[126:127], v[126:127], 0 op_sel_hi:[1,0]
	v_pk_add_f32 v[124:125], v[124:125], 0 op_sel_hi:[1,0]
	v_pk_add_f32 v[122:123], v[122:123], 0 op_sel_hi:[1,0]
	v_pk_add_f32 v[144:145], v[112:113], 0 op_sel_hi:[1,0]
	v_pk_add_f32 v[150:151], v[110:111], 0 op_sel_hi:[1,0]
	v_pk_add_f32 v[152:153], v[104:105], 0 op_sel_hi:[1,0]
	v_pk_add_f32 v[154:155], v[102:103], 0 op_sel_hi:[1,0]
	v_pk_add_f32 v[102:103], v[120:121], 0 op_sel_hi:[1,0]
	v_pk_add_f32 v[104:105], v[118:119], 0 op_sel_hi:[1,0]
	v_pk_add_f32 v[110:111], v[116:117], 0 op_sel_hi:[1,0]
	v_pk_add_f32 v[112:113], v[114:115], 0 op_sel_hi:[1,0]
	v_pk_add_f32 v[114:115], v[96:97], 0 op_sel_hi:[1,0]
	v_pk_add_f32 v[116:117], v[94:95], 0 op_sel_hi:[1,0]
	v_pk_add_f32 v[118:119], v[88:89], 0 op_sel_hi:[1,0]
	v_pk_add_f32 v[120:121], v[86:87], 0 op_sel_hi:[1,0]
	v_pk_add_f32 v[86:87], v[108:109], 0 op_sel_hi:[1,0]
	v_pk_add_f32 v[88:89], v[106:107], 0 op_sel_hi:[1,0]
	v_pk_add_f32 v[94:95], v[100:101], 0 op_sel_hi:[1,0]
	v_pk_add_f32 v[96:97], v[98:99], 0 op_sel_hi:[1,0]
	v_pk_add_f32 v[98:99], v[80:81], 0 op_sel_hi:[1,0]
	v_pk_add_f32 v[100:101], v[78:79], 0 op_sel_hi:[1,0]
	v_pk_add_f32 v[106:107], v[76:77], 0 op_sel_hi:[1,0]
	v_pk_add_f32 v[108:109], v[74:75], 0 op_sel_hi:[1,0]
	v_pk_add_f32 v[74:75], v[92:93], 0 op_sel_hi:[1,0]
	v_pk_add_f32 v[76:77], v[90:91], 0 op_sel_hi:[1,0]
	v_pk_add_f32 v[78:79], v[84:85], 0 op_sel_hi:[1,0]
	v_pk_add_f32 v[80:81], v[82:83], 0 op_sel_hi:[1,0]
	v_pk_add_f32 v[72:73], v[72:73], 0 op_sel_hi:[1,0]
	v_pk_add_f32 v[70:71], v[70:71], 0 op_sel_hi:[1,0]
	v_pk_add_f32 v[68:69], v[68:69], 0 op_sel_hi:[1,0]
	v_pk_add_f32 v[66:67], v[66:67], 0 op_sel_hi:[1,0]
	v_pk_add_f32 v[64:65], v[64:65], 0 op_sel_hi:[1,0]
	v_pk_add_f32 v[62:63], v[62:63], 0 op_sel_hi:[1,0]
	v_pk_add_f32 v[60:61], v[60:61], 0 op_sel_hi:[1,0]
	v_pk_add_f32 v[58:59], v[58:59], 0 op_sel_hi:[1,0]
	v_pk_add_f32 v[82:83], v[48:49], 0 op_sel_hi:[1,0]
	v_pk_add_f32 v[84:85], v[46:47], 0 op_sel_hi:[1,0]
	v_pk_add_f32 v[90:91], v[40:41], 0 op_sel_hi:[1,0]
	v_pk_add_f32 v[92:93], v[38:39], 0 op_sel_hi:[1,0]
	v_pk_add_f32 v[38:39], v[56:57], 0 op_sel_hi:[1,0]
	v_pk_add_f32 v[40:41], v[54:55], 0 op_sel_hi:[1,0]
	v_pk_add_f32 v[46:47], v[52:53], 0 op_sel_hi:[1,0]
	v_pk_add_f32 v[48:49], v[50:51], 0 op_sel_hi:[1,0]
	v_pk_add_f32 v[50:51], v[32:33], 0 op_sel_hi:[1,0]
	v_pk_add_f32 v[52:53], v[30:31], 0 op_sel_hi:[1,0]
	v_pk_add_f32 v[54:55], v[24:25], 0 op_sel_hi:[1,0]
	v_pk_add_f32 v[56:57], v[22:23], 0 op_sel_hi:[1,0]
	v_pk_add_f32 v[22:23], v[44:45], 0 op_sel_hi:[1,0]
	v_pk_add_f32 v[24:25], v[42:43], 0 op_sel_hi:[1,0]
	v_pk_add_f32 v[30:31], v[36:37], 0 op_sel_hi:[1,0]
	v_pk_add_f32 v[32:33], v[34:35], 0 op_sel_hi:[1,0]
	v_pk_add_f32 v[34:35], v[16:17], 0 op_sel_hi:[1,0]
	v_pk_add_f32 v[36:37], v[14:15], 0 op_sel_hi:[1,0]
	v_pk_add_f32 v[42:43], v[12:13], 0 op_sel_hi:[1,0]
	v_pk_add_f32 v[44:45], v[10:11], 0 op_sel_hi:[1,0]
	v_pk_add_f32 v[10:11], v[28:29], 0 op_sel_hi:[1,0]
	v_pk_add_f32 v[12:13], v[26:27], 0 op_sel_hi:[1,0]
	v_pk_add_f32 v[14:15], v[20:21], 0 op_sel_hi:[1,0]
	v_pk_add_f32 v[16:17], v[18:19], 0 op_sel_hi:[1,0]
	v_pk_add_f32 v[8:9], v[8:9], 0 op_sel_hi:[1,0]
	v_pk_add_f32 v[6:7], v[6:7], 0 op_sel_hi:[1,0]
	v_pk_add_f32 v[4:5], v[4:5], 0 op_sel_hi:[1,0]
	v_pk_add_f32 v[2:3], v[2:3], 0 op_sel_hi:[1,0]

; #define GAS __attribute__((address_space(1)))
; #define AT_ISSUE(t, slot) do { _Pragma("unroll") for (int k_ = 0; k_ < 3; ++k_) glds16(src[k_] + (size_t)(t) * stride[k_], (unsigned)__builtin_amdgcn_readfirstlane(dsto[k_] + (slot) * AT_SLOT)); } while (0)
; __device__ __forceinline__ void glds16(const GAS void* gsrc, unsigned lds_dst) {
;     unsigned keep;
;     asm volatile("s_mov_b32 %0, m0\n\ts_mov_b32 m0, %2\n\ts_nop 0\n\tglobal_load_lds_dwordx4 %1, off\n\ts_mov_b32 m0, %0" : "=&s"(keep) : "v"(gsrc), "s"(lds_dst) : "memory");
; __device__ __forceinline__ void attn_unit(LAS unsigned char* lds, const GAS bf16_t* __restrict__ QR, const GAS float* __restrict__ ssq, const GAS float* __restrict__ RT, const GAS bf16_t* __restrict__ K, const GAS bf16_t* __restrict__ Vt, GAS bf16_t* __restrict__ A2, int b, int h, int qb, int tid, i ...
;     ...
;     f32x16 oA0, oA1, oB0, oB1;
; #pragma unroll
;     for (int i = 0; i < 16; ++i) { oA0[i] = 0.f; oA1[i] = 0.f; oB0[i] = 0.f; oB1[i] = 0.f; }
;     float mA = -1e30f, mB = -1e30f, lA = 0.f, lB = 0.f;
;     constexpr int NT_ = KVLEN / 64;
;     AT_ISSUE(0, 0); AT_ISSUE(1, 1);
;     int slot = 0, nslot = 2;
; #pragma unroll 1
;     for (int t = 0; t < NT_; ++t) {
;         if (t + 1 < NT_) asm volatile("s_waitcnt vmcnt(3) lgkmcnt(0)\n\ts_barrier" ::: "memory"); else asm volatile("s_waitcnt vmcnt(0) lgkmcnt(0)\n\ts_barrier" ::: "memory");
;         if (t + 2 < NT_) AT_ISSUE(t + 2, nslot);
.LBB0_135:
	s_cmpk_eq_i32 s49, 0x83
	s_mov_b64 s[56:57], -1
	s_cbranch_scc1 .LBB0_147
	s_waitcnt vmcnt(3) lgkmcnt(0)
	s_barrier
.LBB0_137:
	s_cmpk_gt_u32 s49, 0x81
	s_cbranch_scc1 .LBB0_139
.LBB0_138:
	s_mul_i32 s22, s50, 0x5800
	s_add_i32 s23, s22, s60
	s_mov_b32 m0, s23
	s_nop 0
	global_load_lds_dwordx4 v[184:185], off
	s_add_i32 s23, s22, s40
	s_mov_b32 m0, s23
	s_nop 0
	global_load_lds_dwordx4 v[182:183], off
	s_add_i32 s22, s22, s41
	s_mov_b32 m0, s22
	s_nop 0
	global_load_lds_dwordx4 v[180:181], off
